# up-projection GEMM K-loop: removed the full load-queue drain hipcc placed at the top of every iteration (the eight other instances of the same loop do not have it)
# speedup vs baseline: 1.0036x; 1.0036x over previous
.LBB0_81:
	s_add_u32 s6, s10, 0x100
	s_addc_u32 s7, s11, 0
	s_add_i32 s80, 0, 0x10000
	s_cmp_eq_u32 s86, 12
	s_cselect_b32 s51, s67, s7
	s_cselect_b32 s50, s66, s6
	s_cselect_b32 s49, s9, vcc_hi
	s_cselect_b32 s48, s65, vcc_lo
	s_add_i32 s58, 0, 0x14000
	v_add_u32_e32 v58, s80, v241
	v_add_u32_e32 v82, s58, v241
	ds_read_b128 v[42:45], v58
	ds_read_b128 v[46:49], v58 offset:1024
	ds_read_b128 v[50:53], v58 offset:2048
	ds_read_b128 v[58:61], v58 offset:3072
	ds_read_b128 v[70:73], v82
	ds_read_b128 v[74:77], v82 offset:1024
	ds_read_b128 v[78:81], v82 offset:2048
	ds_read_b128 v[82:85], v82 offset:3072
	v_lshl_add_u64 v[204:205], s[10:11], 0, v[202:203]
	s_add_i32 m0, s40, 0xc000
	ds_read_b128 v[98:101], v242
	ds_read_b128 v[122:125], v242 offset:1024
	ds_read_b128 v[134:137], v242 offset:2048
	ds_read_b128 v[174:177], v242 offset:3072
	ds_read_b128 v[178:181], v242 offset:4096
	ds_read_b128 v[182:185], v242 offset:5120
	ds_read_b128 v[186:189], v242 offset:6144
	ds_read_b128 v[190:193], v242 offset:7168
	global_load_lds_dwordx4 v[204:205], off
	v_lshl_add_u64 v[204:205], s[10:11], 0, v[222:223]
	s_add_i32 m0, s40, 0xe000
	s_nop 0
	global_load_lds_dwordx4 v[204:205], off
	s_waitcnt vmcnt(8)
	s_waitcnt lgkmcnt(0)
	s_barrier
	s_setprio 1
	s_waitcnt lgkmcnt(0)
	v_mfma_f32_16x16x32_bf16 v[170:173], v[42:45], v[98:101], v[170:173]
	v_mfma_f32_16x16x32_bf16 v[166:169], v[50:53], v[98:101], v[166:169]
	v_mfma_f32_16x16x32_bf16 v[154:157], v[42:45], v[134:137], v[154:157]
	v_mfma_f32_16x16x32_bf16 v[150:153], v[50:53], v[134:137], v[150:153]
	v_mfma_f32_16x16x32_bf16 v[138:141], v[42:45], v[178:181], v[138:141]
	v_mfma_f32_16x16x32_bf16 v[130:133], v[50:53], v[178:181], v[130:133]
	v_mfma_f32_16x16x32_bf16 v[118:121], v[42:45], v[186:189], v[118:121]
	v_mfma_f32_16x16x32_bf16 v[110:113], v[50:53], v[186:189], v[110:113]
	v_mfma_f32_16x16x32_bf16 v[170:173], v[46:49], v[122:125], v[170:173]
	v_mfma_f32_16x16x32_bf16 v[166:169], v[58:61], v[122:125], v[166:169]
	v_mfma_f32_16x16x32_bf16 v[154:157], v[46:49], v[174:177], v[154:157]
	v_mfma_f32_16x16x32_bf16 v[150:153], v[58:61], v[174:177], v[150:153]
	v_mfma_f32_16x16x32_bf16 v[138:141], v[46:49], v[182:185], v[138:141]
	v_mfma_f32_16x16x32_bf16 v[130:133], v[58:61], v[182:185], v[130:133]
	v_mfma_f32_16x16x32_bf16 v[118:121], v[46:49], v[190:193], v[118:121]
	v_mfma_f32_16x16x32_bf16 v[110:113], v[58:61], v[190:193], v[110:113]
	s_setprio 0
	s_setprio 1
	v_mfma_f32_16x16x32_bf16 v[158:161], v[70:73], v[98:101], v[158:161]
	v_mfma_f32_16x16x32_bf16 v[98:101], v[78:81], v[98:101], v[162:165]
	v_mfma_f32_16x16x32_bf16 v[114:117], v[70:73], v[178:181], v[114:117]
	v_mfma_f32_16x16x32_bf16 v[126:129], v[78:81], v[178:181], v[126:129]
	v_mfma_f32_16x16x32_bf16 v[102:105], v[70:73], v[186:189], v[102:105]
	v_mfma_f32_16x16x32_bf16 v[106:109], v[78:81], v[186:189], v[106:109]
	v_mfma_f32_16x16x32_bf16 v[158:161], v[74:77], v[122:125], v[158:161]
	v_mfma_f32_16x16x32_bf16 v[98:101], v[82:85], v[122:125], v[98:101]
	v_mfma_f32_16x16x32_bf16 v[122:125], v[70:73], v[134:137], v[142:145]
	v_mfma_f32_16x16x32_bf16 v[134:137], v[78:81], v[134:137], v[146:149]
	v_mfma_f32_16x16x32_bf16 v[114:117], v[74:77], v[182:185], v[114:117]
	v_mfma_f32_16x16x32_bf16 v[126:129], v[82:85], v[182:185], v[126:129]
	v_mfma_f32_16x16x32_bf16 v[102:105], v[74:77], v[190:193], v[102:105]
	v_mfma_f32_16x16x32_bf16 v[106:109], v[82:85], v[190:193], v[106:109]
	v_mfma_f32_16x16x32_bf16 v[122:125], v[74:77], v[174:177], v[122:125]
	v_mfma_f32_16x16x32_bf16 v[134:137], v[82:85], v[174:177], v[134:137]
	s_setprio 0
	s_barrier
	s_add_i32 s10, s80, s37
	v_lshl_add_u64 v[208:209], s[48:49], 0, v[196:197]
	s_mov_b32 m0, s10
	ds_read_b128 v[142:145], v242 offset:16384
	ds_read_b128 v[146:149], v242 offset:17408
	ds_read_b128 v[162:165], v242 offset:18432
	ds_read_b128 v[174:177], v242 offset:19456
	ds_read_b128 v[178:181], v242 offset:20480
	ds_read_b128 v[182:185], v242 offset:21504
	ds_read_b128 v[186:189], v242 offset:22528
	ds_read_b128 v[190:193], v242 offset:23552
	global_load_lds_dwordx4 v[208:209], off
	s_add_i32 m0, s10, 0x2000
	s_add_u32 s10, s48, 0x40000
	v_lshl_add_u64 v[210:211], s[48:49], 0, v[200:201]
	s_addc_u32 s11, s49, 0
	s_add_i32 s58, s58, s37
	global_load_lds_dwordx4 v[210:211], off
	v_lshl_add_u64 v[204:205], s[10:11], 0, v[196:197]
	s_mov_b32 m0, s58
	v_lshl_add_u64 v[212:213], s[50:51], 0, v[194:195]
	global_load_lds_dwordx4 v[204:205], off
	v_lshl_add_u64 v[204:205], s[10:11], 0, v[200:201]
	s_add_i32 m0, s58, 0x2000
	v_lshl_add_u64 v[214:215], s[50:51], 0, v[198:199]
	global_load_lds_dwordx4 v[204:205], off
	s_mov_b32 m0, s40
	s_nop 0
	global_load_lds_dwordx4 v[212:213], off
	s_mov_b32 m0, s57
	s_nop 0
	global_load_lds_dwordx4 v[214:215], off
	s_waitcnt vmcnt(8)
	s_waitcnt lgkmcnt(0)
	s_barrier
	s_setprio 1
	s_waitcnt lgkmcnt(0)
	v_mfma_f32_16x16x32_bf16 v[94:97], v[42:45], v[142:145], v[94:97]
	v_mfma_f32_16x16x32_bf16 v[90:93], v[50:53], v[142:145], v[90:93]
	v_mfma_f32_16x16x32_bf16 v[62:65], v[42:45], v[162:165], v[62:65]
	v_mfma_f32_16x16x32_bf16 v[54:57], v[50:53], v[162:165], v[54:57]
	v_mfma_f32_16x16x32_bf16 v[30:33], v[42:45], v[178:181], v[30:33]
	v_mfma_f32_16x16x32_bf16 v[26:29], v[50:53], v[178:181], v[26:29]
	v_mfma_f32_16x16x32_bf16 v[18:21], v[42:45], v[186:189], v[18:21]
	v_mfma_f32_16x16x32_bf16 v[10:13], v[50:53], v[186:189], v[10:13]
	v_mfma_f32_16x16x32_bf16 v[94:97], v[46:49], v[146:149], v[94:97]
	v_mfma_f32_16x16x32_bf16 v[90:93], v[58:61], v[146:149], v[90:93]
	v_mfma_f32_16x16x32_bf16 v[62:65], v[46:49], v[174:177], v[62:65]
	v_mfma_f32_16x16x32_bf16 v[54:57], v[58:61], v[174:177], v[54:57]
	v_mfma_f32_16x16x32_bf16 v[30:33], v[46:49], v[182:185], v[30:33]
	v_mfma_f32_16x16x32_bf16 v[26:29], v[58:61], v[182:185], v[26:29]
	v_mfma_f32_16x16x32_bf16 v[18:21], v[46:49], v[190:193], v[18:21]
	v_mfma_f32_16x16x32_bf16 v[10:13], v[58:61], v[190:193], v[10:13]
	s_setprio 0
	s_setprio 1
	v_mfma_f32_16x16x32_bf16 v[34:37], v[70:73], v[162:165], v[34:37]
	v_mfma_f32_16x16x32_bf16 v[38:41], v[78:81], v[162:165], v[38:41]
	v_mfma_f32_16x16x32_bf16 v[14:17], v[70:73], v[178:181], v[14:17]
	v_mfma_f32_16x16x32_bf16 v[22:25], v[78:81], v[178:181], v[22:25]
	v_mfma_f32_16x16x32_bf16 v[2:5], v[70:73], v[186:189], v[2:5]
	v_mfma_f32_16x16x32_bf16 v[6:9], v[78:81], v[186:189], v[6:9]
	v_mfma_f32_16x16x32_bf16 v[42:45], v[70:73], v[142:145], v[66:69]
	v_mfma_f32_16x16x32_bf16 v[46:49], v[78:81], v[142:145], v[86:89]
	v_mfma_f32_16x16x32_bf16 v[34:37], v[74:77], v[174:177], v[34:37]
	v_mfma_f32_16x16x32_bf16 v[38:41], v[82:85], v[174:177], v[38:41]
	v_mfma_f32_16x16x32_bf16 v[14:17], v[74:77], v[182:185], v[14:17]
	v_mfma_f32_16x16x32_bf16 v[22:25], v[82:85], v[182:185], v[22:25]
	v_mfma_f32_16x16x32_bf16 v[2:5], v[74:77], v[190:193], v[2:5]
	v_mfma_f32_16x16x32_bf16 v[6:9], v[82:85], v[190:193], v[6:9]
	v_mfma_f32_16x16x32_bf16 v[42:45], v[74:77], v[146:149], v[42:45]
	v_mfma_f32_16x16x32_bf16 v[46:49], v[82:85], v[146:149], v[46:49]
	s_setprio 0
	s_barrier
	s_add_i32 s58, 0, 0x18000
	s_add_i32 s80, 0, 0x1c000
	v_add_u32_e32 v70, s58, v241
	v_add_u32_e32 v86, s80, v241
	ds_read_b128 v[50:53], v70
	ds_read_b128 v[58:61], v70 offset:1024
	ds_read_b128 v[66:69], v70 offset:2048
	ds_read_b128 v[70:73], v70 offset:3072
	ds_read_b128 v[74:77], v86
	ds_read_b128 v[78:81], v86 offset:1024
	ds_read_b128 v[82:85], v86 offset:2048
	ds_read_b128 v[174:177], v86 offset:3072
	s_add_u32 s10, s50, 0x40000
	s_addc_u32 s11, s51, 0
	s_mov_b32 m0, s74
	v_lshl_add_u64 v[162:163], s[10:11], 0, v[194:195]
	ds_read_b128 v[86:89], v242 offset:32768
	ds_read_b128 v[142:145], v242 offset:33792
	ds_read_b128 v[146:149], v242 offset:34816
	ds_read_b128 v[178:181], v242 offset:35840
	ds_read_b128 v[182:185], v242 offset:36864
	ds_read_b128 v[186:189], v242 offset:37888
	ds_read_b128 v[190:193], v242 offset:38912
	ds_read_b128 v[204:207], v242 offset:39936
	global_load_lds_dwordx4 v[162:163], off
	v_lshl_add_u64 v[162:163], s[10:11], 0, v[198:199]
	s_mov_b32 m0, s75
	s_nop 0
	global_load_lds_dwordx4 v[162:163], off
	s_waitcnt vmcnt(8)
	s_waitcnt lgkmcnt(0)
	s_barrier
	s_setprio 1
	s_waitcnt lgkmcnt(0)
	v_mfma_f32_16x16x32_bf16 v[162:165], v[50:53], v[86:89], v[170:173]
	v_mfma_f32_16x16x32_bf16 v[170:173], v[58:61], v[142:145], v[162:165]
	v_mfma_f32_16x16x32_bf16 v[162:165], v[66:69], v[86:89], v[166:169]
	v_mfma_f32_16x16x32_bf16 v[154:157], v[50:53], v[146:149], v[154:157]
	v_mfma_f32_16x16x32_bf16 v[150:153], v[66:69], v[146:149], v[150:153]
	v_mfma_f32_16x16x32_bf16 v[138:141], v[50:53], v[182:185], v[138:141]
	v_mfma_f32_16x16x32_bf16 v[130:133], v[66:69], v[182:185], v[130:133]
	v_mfma_f32_16x16x32_bf16 v[118:121], v[50:53], v[190:193], v[118:121]
	v_mfma_f32_16x16x32_bf16 v[110:113], v[66:69], v[190:193], v[110:113]
	v_mfma_f32_16x16x32_bf16 v[166:169], v[70:73], v[142:145], v[162:165]
	v_mfma_f32_16x16x32_bf16 v[154:157], v[58:61], v[178:181], v[154:157]
	v_mfma_f32_16x16x32_bf16 v[150:153], v[70:73], v[178:181], v[150:153]
	v_mfma_f32_16x16x32_bf16 v[138:141], v[58:61], v[186:189], v[138:141]
	v_mfma_f32_16x16x32_bf16 v[130:133], v[70:73], v[186:189], v[130:133]
	v_mfma_f32_16x16x32_bf16 v[118:121], v[58:61], v[204:207], v[118:121]
	v_mfma_f32_16x16x32_bf16 v[110:113], v[70:73], v[204:207], v[110:113]
	s_setprio 0
	s_setprio 1
	v_mfma_f32_16x16x32_bf16 v[158:161], v[74:77], v[86:89], v[158:161]
	v_mfma_f32_16x16x32_bf16 v[86:89], v[82:85], v[86:89], v[98:101]
	v_mfma_f32_16x16x32_bf16 v[162:165], v[174:177], v[142:145], v[86:89]
	v_mfma_f32_16x16x32_bf16 v[86:89], v[74:77], v[146:149], v[122:125]
	v_mfma_f32_16x16x32_bf16 v[158:161], v[78:81], v[142:145], v[158:161]
	v_mfma_f32_16x16x32_bf16 v[142:145], v[78:81], v[178:181], v[86:89]
	v_mfma_f32_16x16x32_bf16 v[86:89], v[82:85], v[146:149], v[134:137]
	v_mfma_f32_16x16x32_bf16 v[146:149], v[174:177], v[178:181], v[86:89]
	v_mfma_f32_16x16x32_bf16 v[86:89], v[74:77], v[182:185], v[114:117]
	v_mfma_f32_16x16x32_bf16 v[114:117], v[78:81], v[186:189], v[86:89]
	v_mfma_f32_16x16x32_bf16 v[86:89], v[82:85], v[182:185], v[126:129]
	v_mfma_f32_16x16x32_bf16 v[126:129], v[174:177], v[186:189], v[86:89]
	v_mfma_f32_16x16x32_bf16 v[86:89], v[74:77], v[190:193], v[102:105]
	v_mfma_f32_16x16x32_bf16 v[102:105], v[78:81], v[204:207], v[86:89]
	v_mfma_f32_16x16x32_bf16 v[86:89], v[82:85], v[190:193], v[106:109]
	v_mfma_f32_16x16x32_bf16 v[106:109], v[174:177], v[204:207], v[86:89]
	s_setprio 0
	s_barrier
	s_add_i32 s10, s58, s37
	v_lshl_add_u64 v[204:205], v[208:209], 0, s[42:43]
	s_mov_b32 m0, s10
	s_nop 1
	ds_read_b128 v[86:89], v242 offset:49152
	ds_read_b128 v[98:101], v242 offset:50176
	ds_read_b128 v[122:125], v242 offset:51200
	ds_read_b128 v[134:137], v242 offset:52224
	ds_read_b128 v[178:181], v242 offset:53248
	ds_read_b128 v[182:185], v242 offset:54272
	ds_read_b128 v[186:189], v242 offset:55296
	ds_read_b128 v[190:193], v242 offset:56320
	global_load_lds_dwordx4 v[204:205], off
	s_add_i32 m0, s10, 0x2000
	s_add_u32 s10, s48, 0x40080
	v_lshl_add_u64 v[204:205], v[210:211], 0, s[42:43]
	s_addc_u32 s11, s49, 0
	s_add_i32 s48, s80, s37
	global_load_lds_dwordx4 v[204:205], off
	v_lshl_add_u64 v[204:205], s[10:11], 0, v[196:197]
	s_mov_b32 m0, s48
	s_nop 0
	global_load_lds_dwordx4 v[204:205], off
	v_lshl_add_u64 v[204:205], s[10:11], 0, v[200:201]
	s_add_i32 m0, s48, 0x2000
	s_nop 0
	global_load_lds_dwordx4 v[204:205], off
	v_lshl_add_u64 v[204:205], v[212:213], 0, s[42:43]
	s_mov_b32 m0, s93
	s_nop 0
	global_load_lds_dwordx4 v[204:205], off
	v_lshl_add_u64 v[204:205], v[214:215], 0, s[42:43]
	s_mov_b32 m0, s94
	s_nop 0
	global_load_lds_dwordx4 v[204:205], off
	s_waitcnt vmcnt(8)
	s_waitcnt lgkmcnt(0)
	s_barrier
	s_setprio 1
	s_waitcnt lgkmcnt(0)
	v_mfma_f32_16x16x32_bf16 v[94:97], v[50:53], v[86:89], v[94:97]
	v_mfma_f32_16x16x32_bf16 v[90:93], v[66:69], v[86:89], v[90:93]
	v_mfma_f32_16x16x32_bf16 v[62:65], v[50:53], v[122:125], v[62:65]
	v_mfma_f32_16x16x32_bf16 v[54:57], v[66:69], v[122:125], v[54:57]
	v_mfma_f32_16x16x32_bf16 v[30:33], v[50:53], v[178:181], v[30:33]
	v_mfma_f32_16x16x32_bf16 v[26:29], v[66:69], v[178:181], v[26:29]
	v_mfma_f32_16x16x32_bf16 v[18:21], v[50:53], v[186:189], v[18:21]
	v_mfma_f32_16x16x32_bf16 v[10:13], v[66:69], v[186:189], v[10:13]
	v_mfma_f32_16x16x32_bf16 v[94:97], v[58:61], v[98:101], v[94:97]
	v_mfma_f32_16x16x32_bf16 v[90:93], v[70:73], v[98:101], v[90:93]
	v_mfma_f32_16x16x32_bf16 v[62:65], v[58:61], v[134:137], v[62:65]
	v_mfma_f32_16x16x32_bf16 v[54:57], v[70:73], v[134:137], v[54:57]
	v_mfma_f32_16x16x32_bf16 v[30:33], v[58:61], v[182:185], v[30:33]
	v_mfma_f32_16x16x32_bf16 v[26:29], v[70:73], v[182:185], v[26:29]
	v_mfma_f32_16x16x32_bf16 v[18:21], v[58:61], v[190:193], v[18:21]
	v_mfma_f32_16x16x32_bf16 v[10:13], v[70:73], v[190:193], v[10:13]
	s_setprio 0
	s_setprio 1
	v_mfma_f32_16x16x32_bf16 v[42:45], v[74:77], v[86:89], v[42:45]
	v_mfma_f32_16x16x32_bf16 v[66:69], v[78:81], v[98:101], v[42:45]
	v_mfma_f32_16x16x32_bf16 v[42:45], v[82:85], v[86:89], v[46:49]
	v_mfma_f32_16x16x32_bf16 v[34:37], v[74:77], v[122:125], v[34:37]
	v_mfma_f32_16x16x32_bf16 v[38:41], v[82:85], v[122:125], v[38:41]
	v_mfma_f32_16x16x32_bf16 v[14:17], v[74:77], v[178:181], v[14:17]
	v_mfma_f32_16x16x32_bf16 v[22:25], v[82:85], v[178:181], v[22:25]
	v_mfma_f32_16x16x32_bf16 v[2:5], v[74:77], v[186:189], v[2:5]
	v_mfma_f32_16x16x32_bf16 v[6:9], v[82:85], v[186:189], v[6:9]
	v_mfma_f32_16x16x32_bf16 v[86:89], v[174:177], v[98:101], v[42:45]
	v_mfma_f32_16x16x32_bf16 v[34:37], v[78:81], v[134:137], v[34:37]
	v_mfma_f32_16x16x32_bf16 v[38:41], v[174:177], v[134:137], v[38:41]
	v_mfma_f32_16x16x32_bf16 v[14:17], v[78:81], v[182:185], v[14:17]
	v_mfma_f32_16x16x32_bf16 v[22:25], v[174:177], v[182:185], v[22:25]
	v_mfma_f32_16x16x32_bf16 v[2:5], v[78:81], v[190:193], v[2:5]
	v_mfma_f32_16x16x32_bf16 v[6:9], v[174:177], v[190:193], v[6:9]
	s_setprio 0
	s_barrier
	s_add_i32 s86, s86, 2
	s_add_u32 vcc_lo, vcc_lo, 0x100
	s_addc_u32 vcc_hi, vcc_hi, 0
	s_cmp_gt_u32 s86, 13
	s_mov_b64 s[10:11], s[6:7]
	s_cbranch_scc0 .LBB0_81
	s_mul_i32 s48, s36, 0xfe
	v_mov_b32_e32 v42, v1
	s_add_i32 s6, s95, s48
	v_mov_b32_e32 v49, 0x3fff
	v_add_u32_e32 v46, s6, v42
	v_add_u32_e32 v43, 16, v46
	v_med3_i32 v42, v46, 0, v49
	v_med3_i32 v43, v43, 0, v49
	v_lshlrev_b32_e32 v42, 4, v42
	v_lshlrev_b32_e32 v43, 4, v43
	global_load_dwordx4 v[182:185], v42, s[18:19]
	global_load_dwordx4 v[178:181], v43, s[18:19]
	v_add_u32_e32 v42, 32, v46
	v_add_u32_e32 v43, 48, v46
	v_add_u32_e32 v47, 0x80, v46
	v_med3_i32 v42, v42, 0, v49
	v_med3_i32 v43, v43, 0, v49
	v_med3_i32 v47, v47, 0, v49
	v_add_u32_e32 v48, 0x90, v46
	v_lshlrev_b32_e32 v42, 4, v42
	v_lshlrev_b32_e32 v43, 4, v43
	v_lshlrev_b32_e32 v47, 4, v47
	v_med3_i32 v48, v48, 0, v49
	global_load_dwordx4 v[174:177], v42, s[18:19]
	s_nop 0
	global_load_dwordx4 v[42:45], v43, s[18:19]
	v_lshlrev_b32_e32 v48, 4, v48
	global_load_dwordx4 v[134:137], v47, s[18:19]
	global_load_dwordx4 v[122:125], v48, s[18:19]
	v_add_u32_e32 v47, 0xa0, v46
	v_add_u32_e32 v46, 0xb0, v46
	v_med3_i32 v47, v47, 0, v49
	v_med3_i32 v46, v46, 0, v49
	v_lshlrev_b32_e32 v47, 4, v47
	v_lshlrev_b32_e32 v46, 4, v46
	global_load_dwordx4 v[98:101], v47, s[18:19]
	s_nop 0
	global_load_dwordx4 v[46:49], v46, s[18:19]
	s_and_b64 vcc, exec, s[26:27]
	s_cbranch_vccz .LBB0_84
	s_barrier
